# v94 + mLSTM scan S1/S3 k-loops fully unrolled with immediate LDS offsets (no per-iteration address adds / loop control)
# baseline (speedup 1.0000x reference)
.Lpf_skip:
.LBB0_209:
	v_add_u32_e32 v245, 0x1dc00, v212
	ds_read_b128 v[120:123], v214 offset:34816
	ds_read_b128 v[124:127], v213
	ds_read_b128 v[220:223], v213 offset:4352
	ds_read_b128 v[224:227], v213 offset:8704
	ds_read_b128 v[228:231], v213 offset:13056
	ds_read_b128 v[232:235], v214
	ds_read_b128 v[246:249], v245
	ds_read_b128 v[236:239], v245 offset:4352
	ds_read_b128 v[250:253], v214 offset:39168
	s_waitcnt lgkmcnt(7)
	v_mfma_f32_16x16x32_bf16 v[116:119], v[120:123], v[124:127], v[116:119]
	s_waitcnt lgkmcnt(6)
	v_mfma_f32_16x16x32_bf16 v[112:115], v[120:123], v[220:223], v[112:115]
	s_waitcnt lgkmcnt(5)
	v_mfma_f32_16x16x32_bf16 v[104:107], v[120:123], v[224:227], v[104:107]
	s_waitcnt lgkmcnt(4)
	v_mfma_f32_16x16x32_bf16 v[96:99], v[120:123], v[228:231], v[96:99]
	ds_read_b128 v[120:123], v214 offset:4352
	s_waitcnt lgkmcnt(3)
	v_mfma_f32_16x16x32_bf16 v[84:87], v[232:235], v[246:249], v[84:87]
	s_waitcnt lgkmcnt(2)
	v_mfma_f32_16x16x32_bf16 v[80:83], v[232:235], v[236:239], v[80:83]
	s_waitcnt lgkmcnt(1)
	v_mfma_f32_16x16x32_bf16 v[108:111], v[250:253], v[124:127], v[108:111]
	v_mfma_f32_16x16x32_bf16 v[100:103], v[250:253], v[220:223], v[100:103]
	v_mfma_f32_16x16x32_bf16 v[92:95], v[250:253], v[224:227], v[92:95]
	v_mfma_f32_16x16x32_bf16 v[88:91], v[250:253], v[228:231], v[88:91]
	s_waitcnt lgkmcnt(0)
	v_mfma_f32_16x16x32_bf16 v[76:79], v[120:123], v[246:249], v[76:79]
	v_mfma_f32_16x16x32_bf16 v[72:75], v[120:123], v[236:239], v[72:75]
	ds_read_b128 v[120:123], v214 offset:34880
	ds_read_b128 v[124:127], v213 offset:64
	ds_read_b128 v[220:223], v213 offset:4416
	ds_read_b128 v[224:227], v213 offset:8768
	ds_read_b128 v[228:231], v213 offset:13120
	ds_read_b128 v[232:235], v214 offset:64
	ds_read_b128 v[246:249], v245 offset:64
	ds_read_b128 v[236:239], v245 offset:4416
	ds_read_b128 v[250:253], v214 offset:39232
	s_waitcnt lgkmcnt(7)
	v_mfma_f32_16x16x32_bf16 v[116:119], v[120:123], v[124:127], v[116:119]
	s_waitcnt lgkmcnt(6)
	v_mfma_f32_16x16x32_bf16 v[112:115], v[120:123], v[220:223], v[112:115]
	s_waitcnt lgkmcnt(5)
	v_mfma_f32_16x16x32_bf16 v[104:107], v[120:123], v[224:227], v[104:107]
	s_waitcnt lgkmcnt(4)
	v_mfma_f32_16x16x32_bf16 v[96:99], v[120:123], v[228:231], v[96:99]
	ds_read_b128 v[120:123], v214 offset:4416
	s_waitcnt lgkmcnt(3)
	v_mfma_f32_16x16x32_bf16 v[84:87], v[232:235], v[246:249], v[84:87]
	s_waitcnt lgkmcnt(2)
	v_mfma_f32_16x16x32_bf16 v[80:83], v[232:235], v[236:239], v[80:83]
	s_waitcnt lgkmcnt(1)
	v_mfma_f32_16x16x32_bf16 v[108:111], v[250:253], v[124:127], v[108:111]
	v_mfma_f32_16x16x32_bf16 v[100:103], v[250:253], v[220:223], v[100:103]
	v_mfma_f32_16x16x32_bf16 v[92:95], v[250:253], v[224:227], v[92:95]
	v_mfma_f32_16x16x32_bf16 v[88:91], v[250:253], v[228:231], v[88:91]
	s_waitcnt lgkmcnt(0)
	v_mfma_f32_16x16x32_bf16 v[76:79], v[120:123], v[246:249], v[76:79]
	v_mfma_f32_16x16x32_bf16 v[72:75], v[120:123], v[236:239], v[72:75]
	ds_read_b128 v[120:123], v214 offset:34944
	ds_read_b128 v[124:127], v213 offset:128
	ds_read_b128 v[220:223], v213 offset:4480
	ds_read_b128 v[224:227], v213 offset:8832
	ds_read_b128 v[228:231], v213 offset:13184
	ds_read_b128 v[232:235], v214 offset:128
	ds_read_b128 v[246:249], v245 offset:128
	ds_read_b128 v[236:239], v245 offset:4480
	ds_read_b128 v[250:253], v214 offset:39296
	s_waitcnt lgkmcnt(7)
	v_mfma_f32_16x16x32_bf16 v[116:119], v[120:123], v[124:127], v[116:119]
	s_waitcnt lgkmcnt(6)
	v_mfma_f32_16x16x32_bf16 v[112:115], v[120:123], v[220:223], v[112:115]
	s_waitcnt lgkmcnt(5)
	v_mfma_f32_16x16x32_bf16 v[104:107], v[120:123], v[224:227], v[104:107]
	s_waitcnt lgkmcnt(4)
	v_mfma_f32_16x16x32_bf16 v[96:99], v[120:123], v[228:231], v[96:99]
	ds_read_b128 v[120:123], v214 offset:4480
	s_waitcnt lgkmcnt(3)
	v_mfma_f32_16x16x32_bf16 v[84:87], v[232:235], v[246:249], v[84:87]
	s_waitcnt lgkmcnt(2)
	v_mfma_f32_16x16x32_bf16 v[80:83], v[232:235], v[236:239], v[80:83]
	s_waitcnt lgkmcnt(1)
	v_mfma_f32_16x16x32_bf16 v[108:111], v[250:253], v[124:127], v[108:111]
	v_mfma_f32_16x16x32_bf16 v[100:103], v[250:253], v[220:223], v[100:103]
	v_mfma_f32_16x16x32_bf16 v[92:95], v[250:253], v[224:227], v[92:95]
	v_mfma_f32_16x16x32_bf16 v[88:91], v[250:253], v[228:231], v[88:91]
	s_waitcnt lgkmcnt(0)
	v_mfma_f32_16x16x32_bf16 v[76:79], v[120:123], v[246:249], v[76:79]
	v_mfma_f32_16x16x32_bf16 v[72:75], v[120:123], v[236:239], v[72:75]
	ds_read_b128 v[120:123], v214 offset:35008
	ds_read_b128 v[124:127], v213 offset:192
	ds_read_b128 v[220:223], v213 offset:4544
	ds_read_b128 v[224:227], v213 offset:8896
	ds_read_b128 v[228:231], v213 offset:13248
	ds_read_b128 v[232:235], v214 offset:192
	ds_read_b128 v[246:249], v245 offset:192
	ds_read_b128 v[236:239], v245 offset:4544
	ds_read_b128 v[250:253], v214 offset:39360
	s_waitcnt lgkmcnt(7)
	v_mfma_f32_16x16x32_bf16 v[116:119], v[120:123], v[124:127], v[116:119]
	s_waitcnt lgkmcnt(6)
	v_mfma_f32_16x16x32_bf16 v[112:115], v[120:123], v[220:223], v[112:115]
	s_waitcnt lgkmcnt(5)
	v_mfma_f32_16x16x32_bf16 v[104:107], v[120:123], v[224:227], v[104:107]
	s_waitcnt lgkmcnt(4)
	v_mfma_f32_16x16x32_bf16 v[96:99], v[120:123], v[228:231], v[96:99]
	ds_read_b128 v[120:123], v214 offset:4544
	s_waitcnt lgkmcnt(3)
	v_mfma_f32_16x16x32_bf16 v[84:87], v[232:235], v[246:249], v[84:87]
	s_waitcnt lgkmcnt(2)
	v_mfma_f32_16x16x32_bf16 v[80:83], v[232:235], v[236:239], v[80:83]
	s_waitcnt lgkmcnt(1)
	v_mfma_f32_16x16x32_bf16 v[108:111], v[250:253], v[124:127], v[108:111]
	v_mfma_f32_16x16x32_bf16 v[100:103], v[250:253], v[220:223], v[100:103]
	v_mfma_f32_16x16x32_bf16 v[92:95], v[250:253], v[224:227], v[92:95]
	v_mfma_f32_16x16x32_bf16 v[88:91], v[250:253], v[228:231], v[88:91]
	s_waitcnt lgkmcnt(0)
	v_mfma_f32_16x16x32_bf16 v[76:79], v[120:123], v[246:249], v[76:79]
	v_mfma_f32_16x16x32_bf16 v[72:75], v[120:123], v[236:239], v[72:75]
	ds_read_b128 v[120:123], v169
	ds_read_b128 v[124:127], v169 offset:16
	ds_read_b128 v[220:223], v169 offset:32
	ds_read_b128 v[224:227], v169 offset:48
	ds_read_b128 v[228:231], v170
	ds_read_b128 v[232:235], v170 offset:16
	ds_read_b128 v[236:239], v170 offset:32
	ds_read_b128 v[240:243], v170 offset:48
	ds_read_b128 v[246:249], v170 offset:64
	ds_read_b128 v[250:253], v170 offset:80
	s_waitcnt lgkmcnt(9)
	v_lshlrev_b32_e32 v202, 16, v120
	v_and_b32_e32 v120, 0xffff0000, v120
	s_waitcnt lgkmcnt(5)
	v_mul_f32_e32 v120, v229, v120
	v_fmac_f32_e32 v120, v228, v202
	v_lshlrev_b32_e32 v202, 16, v121
	v_fmac_f32_e32 v120, v230, v202
	v_and_b32_e32 v121, 0xffff0000, v121
	v_fmac_f32_e32 v120, v231, v121
	v_lshlrev_b32_e32 v121, 16, v122
	s_waitcnt lgkmcnt(4)
	v_fmac_f32_e32 v120, v232, v121
	v_and_b32_e32 v121, 0xffff0000, v122
	v_fmac_f32_e32 v120, v233, v121
	v_lshlrev_b32_e32 v121, 16, v123
	v_fmac_f32_e32 v120, v234, v121
	v_and_b32_e32 v121, 0xffff0000, v123
	v_fmac_f32_e32 v120, v235, v121
	v_and_b32_e32 v121, 0xffff0000, v124
	v_add_f32_e32 v202, 0, v120
	v_lshlrev_b32_e32 v120, 16, v124
	s_waitcnt lgkmcnt(3)
	v_mul_f32_e32 v124, v237, v121
	v_fmac_f32_e32 v124, v236, v120
	v_lshlrev_b32_e32 v120, 16, v125
	v_fmac_f32_e32 v124, v238, v120
	v_and_b32_e32 v120, 0xffff0000, v125
	v_fmac_f32_e32 v124, v239, v120
	v_lshlrev_b32_e32 v120, 16, v126
	s_waitcnt lgkmcnt(2)
	v_fmac_f32_e32 v124, v240, v120
	v_and_b32_e32 v120, 0xffff0000, v126
	v_fmac_f32_e32 v124, v241, v120
	v_lshlrev_b32_e32 v120, 16, v127
	v_fmac_f32_e32 v124, v242, v120
	v_and_b32_e32 v120, 0xffff0000, v127
	v_fmac_f32_e32 v124, v243, v120
	ds_read_b128 v[120:123], v170 offset:96
	v_add_f32_e32 v202, v202, v124
	ds_read_b128 v[124:127], v170 offset:112
	v_lshlrev_b32_e32 v219, 16, v220
	v_and_b32_e32 v220, 0xffff0000, v220
	s_waitcnt lgkmcnt(2)
	v_mul_f32_e32 v220, v247, v220
	v_fmac_f32_e32 v220, v246, v219
	v_lshlrev_b32_e32 v245, 16, v221
	v_fmac_f32_e32 v220, v248, v245
	v_and_b32_e32 v245, 0xffff0000, v221
	v_fmac_f32_e32 v220, v249, v245
	v_lshlrev_b32_e32 v245, 16, v222
	s_nop 0
	v_fmac_f32_e32 v220, v250, v245
	v_and_b32_e32 v245, 0xffff0000, v222
	v_fmac_f32_e32 v220, v251, v245
	v_lshlrev_b32_e32 v245, 16, v223
	v_fmac_f32_e32 v220, v252, v245
	v_and_b32_e32 v245, 0xffff0000, v223
	v_fmac_f32_e32 v220, v253, v245
	s_nop 0
	s_nop 0
	v_add_f32_e32 v202, v202, v220
	v_and_b32_e32 v220, 0xffff0000, v224
	v_lshlrev_b32_e32 v219, 16, v224
	s_waitcnt lgkmcnt(1)
	v_mul_f32_e32 v121, v121, v220
	v_fmac_f32_e32 v121, v120, v219
	v_lshlrev_b32_e32 v120, 16, v225
	v_fmac_f32_e32 v121, v122, v120
	v_and_b32_e32 v120, 0xffff0000, v225
	v_fmac_f32_e32 v121, v123, v120
	v_lshlrev_b32_e32 v120, 16, v226
	s_waitcnt lgkmcnt(0)
	v_fmac_f32_e32 v121, v124, v120
	v_and_b32_e32 v120, 0xffff0000, v226
	v_fmac_f32_e32 v121, v125, v120
	v_lshlrev_b32_e32 v120, 16, v227
	v_fmac_f32_e32 v121, v126, v120
	v_and_b32_e32 v120, 0xffff0000, v227
	v_fmac_f32_e32 v121, v127, v120
	v_add_f32_e32 v120, v202, v121
	s_nop 1
	v_add_f32_dpp v120, v120, v120 quad_perm:[1,0,3,2] row_mask:0xf bank_mask:0xf
	s_waitcnt lgkmcnt(0)
	s_nop 1
	v_add_f32_dpp v120, v120, v120 quad_perm:[2,3,0,1] row_mask:0xf bank_mask:0xf
	s_and_saveexec_b64 s[86:87], s[6:7]
	s_cbranch_execz .LBB0_212
	s_waitcnt lgkmcnt(0)
	s_nop 0
	ds_write_b32 v173, v120

.LBB0_227:
	v_add_u32_e32 v89, 0x19800, v212
	v_add_u32_e32 v245, 0x11000, v214
	ds_read_b128 v[90:93], v214 offset:34816
	ds_read_b128 v[94:97], v89
	ds_read_b128 v[98:101], v89 offset:4352
	ds_read_b128 v[246:249], v214 offset:39168
	ds_read_b128 v[250:253], v245
	ds_read_b128 v[102:105], v245 offset:4352
	s_waitcnt lgkmcnt(4)
	v_mfma_f32_16x16x32_bf16 v[84:87], v[90:93], v[94:97], v[84:87]
	s_waitcnt lgkmcnt(3)
	v_mfma_f32_16x16x32_bf16 v[80:83], v[90:93], v[98:101], v[80:83]
	s_waitcnt lgkmcnt(2)
	v_mfma_f32_16x16x32_bf16 v[76:79], v[246:249], v[94:97], v[76:79]
	v_mfma_f32_16x16x32_bf16 v[72:75], v[246:249], v[98:101], v[72:75]
	s_waitcnt lgkmcnt(1)
	v_mfma_f32_16x16x32_bf16 v[56:59], v[250:253], v[94:97], v[56:59]
	v_mfma_f32_16x16x32_bf16 v[60:63], v[250:253], v[98:101], v[60:63]
	s_waitcnt lgkmcnt(0)
	v_mfma_f32_16x16x32_bf16 v[64:67], v[102:105], v[94:97], v[64:67]
	v_mfma_f32_16x16x32_bf16 v[68:71], v[102:105], v[98:101], v[68:71]
	ds_read_b128 v[90:93], v214 offset:34880
	ds_read_b128 v[94:97], v89 offset:64
	ds_read_b128 v[98:101], v89 offset:4416
	ds_read_b128 v[246:249], v214 offset:39232
	ds_read_b128 v[250:253], v245 offset:64
	ds_read_b128 v[102:105], v245 offset:4416
	s_waitcnt lgkmcnt(4)
	v_mfma_f32_16x16x32_bf16 v[84:87], v[90:93], v[94:97], v[84:87]
	s_waitcnt lgkmcnt(3)
	v_mfma_f32_16x16x32_bf16 v[80:83], v[90:93], v[98:101], v[80:83]
	s_waitcnt lgkmcnt(2)
	v_mfma_f32_16x16x32_bf16 v[76:79], v[246:249], v[94:97], v[76:79]
	v_mfma_f32_16x16x32_bf16 v[72:75], v[246:249], v[98:101], v[72:75]
	s_waitcnt lgkmcnt(1)
	v_mfma_f32_16x16x32_bf16 v[56:59], v[250:253], v[94:97], v[56:59]
	v_mfma_f32_16x16x32_bf16 v[60:63], v[250:253], v[98:101], v[60:63]
	s_waitcnt lgkmcnt(0)
	v_mfma_f32_16x16x32_bf16 v[64:67], v[102:105], v[94:97], v[64:67]
	v_mfma_f32_16x16x32_bf16 v[68:71], v[102:105], v[98:101], v[68:71]
	ds_read_b128 v[90:93], v214 offset:34944
	ds_read_b128 v[94:97], v89 offset:128
	ds_read_b128 v[98:101], v89 offset:4480
	ds_read_b128 v[246:249], v214 offset:39296
	ds_read_b128 v[250:253], v245 offset:128
	ds_read_b128 v[102:105], v245 offset:4480
	s_waitcnt lgkmcnt(4)
	v_mfma_f32_16x16x32_bf16 v[84:87], v[90:93], v[94:97], v[84:87]
	s_waitcnt lgkmcnt(3)
	v_mfma_f32_16x16x32_bf16 v[80:83], v[90:93], v[98:101], v[80:83]
	s_waitcnt lgkmcnt(2)
	v_mfma_f32_16x16x32_bf16 v[76:79], v[246:249], v[94:97], v[76:79]
	v_mfma_f32_16x16x32_bf16 v[72:75], v[246:249], v[98:101], v[72:75]
	s_waitcnt lgkmcnt(1)
	v_mfma_f32_16x16x32_bf16 v[56:59], v[250:253], v[94:97], v[56:59]
	v_mfma_f32_16x16x32_bf16 v[60:63], v[250:253], v[98:101], v[60:63]
	s_waitcnt lgkmcnt(0)
	v_mfma_f32_16x16x32_bf16 v[64:67], v[102:105], v[94:97], v[64:67]
	v_mfma_f32_16x16x32_bf16 v[68:71], v[102:105], v[98:101], v[68:71]
	ds_read_b128 v[90:93], v214 offset:35008
	ds_read_b128 v[94:97], v89 offset:192
	ds_read_b128 v[98:101], v89 offset:4544
	ds_read_b128 v[246:249], v214 offset:39360
	ds_read_b128 v[250:253], v245 offset:192
	ds_read_b128 v[102:105], v245 offset:4544
	s_waitcnt lgkmcnt(4)
	v_mfma_f32_16x16x32_bf16 v[84:87], v[90:93], v[94:97], v[84:87]
	s_waitcnt lgkmcnt(3)
	v_mfma_f32_16x16x32_bf16 v[80:83], v[90:93], v[98:101], v[80:83]
	s_waitcnt lgkmcnt(2)
	v_mfma_f32_16x16x32_bf16 v[76:79], v[246:249], v[94:97], v[76:79]
	v_mfma_f32_16x16x32_bf16 v[72:75], v[246:249], v[98:101], v[72:75]
	s_waitcnt lgkmcnt(1)
	v_mfma_f32_16x16x32_bf16 v[56:59], v[250:253], v[94:97], v[56:59]
	v_mfma_f32_16x16x32_bf16 v[60:63], v[250:253], v[98:101], v[60:63]
	s_waitcnt lgkmcnt(0)
	v_mfma_f32_16x16x32_bf16 v[64:67], v[102:105], v[94:97], v[64:67]
	v_mfma_f32_16x16x32_bf16 v[68:71], v[102:105], v[98:101], v[68:71]
	ds_read_b128 v[90:93], v216
	ds_read_b128 v[94:97], v216 offset:16
	ds_read_b128 v[98:101], v216 offset:32
	ds_read_b128 v[102:105], v216 offset:48
	s_lshl_b32 s84, s84, 7
	s_sub_i32 s90, s94, s84
	s_and_b64 s[86:87], s[2:3], exec
	s_waitcnt lgkmcnt(3)
	v_lshlrev_b32_e32 v89, 16, v90
	v_and_b32_e32 v90, 0xffff0000, v90
	v_add_f32_e32 v89, v89, v90
	v_lshlrev_b32_e32 v90, 16, v91
	v_and_b32_e32 v91, 0xffff0000, v91
	v_add_f32_e32 v90, v90, v91
	v_add_f32_e32 v89, v89, v90
	v_lshlrev_b32_e32 v90, 16, v92
	v_and_b32_e32 v91, 0xffff0000, v92
	v_add_f32_e32 v90, v90, v91
	v_add_f32_e32 v89, v90, v89
	v_lshlrev_b32_e32 v90, 16, v93
	v_and_b32_e32 v91, 0xffff0000, v93
	v_add_f32_e32 v90, v90, v91
	v_add_f32_e32 v89, v90, v89
	s_waitcnt lgkmcnt(2)
	v_lshlrev_b32_e32 v90, 16, v94
	v_and_b32_e32 v91, 0xffff0000, v94
	v_add_f32_e32 v90, v90, v91
	v_lshlrev_b32_e32 v91, 16, v95
	v_and_b32_e32 v92, 0xffff0000, v95
	v_add_f32_e32 v91, v91, v92
	v_add_f32_e32 v90, v90, v91
	v_lshlrev_b32_e32 v91, 16, v96
	v_and_b32_e32 v92, 0xffff0000, v96
	v_add_f32_e32 v91, v91, v92
	v_add_f32_e32 v90, v91, v90
	v_lshlrev_b32_e32 v91, 16, v97
	v_and_b32_e32 v92, 0xffff0000, v97
	v_add_f32_e32 v91, v91, v92
	v_add_f32_e32 v89, 0, v89
	v_add_f32_e32 v90, v91, v90
	v_add_f32_e32 v89, v89, v90
	s_waitcnt lgkmcnt(1)
	v_lshlrev_b32_e32 v90, 16, v98
	v_and_b32_e32 v91, 0xffff0000, v98
	v_add_f32_e32 v90, v90, v91
	v_lshlrev_b32_e32 v91, 16, v99
	v_and_b32_e32 v92, 0xffff0000, v99
	v_add_f32_e32 v91, v91, v92
	v_add_f32_e32 v90, v90, v91
	v_lshlrev_b32_e32 v91, 16, v100
	v_and_b32_e32 v92, 0xffff0000, v100
	v_add_f32_e32 v91, v91, v92
	v_add_f32_e32 v90, v91, v90
	v_lshlrev_b32_e32 v91, 16, v101
	v_and_b32_e32 v92, 0xffff0000, v101
	v_add_f32_e32 v91, v91, v92
	v_add_f32_e32 v90, v91, v90
	v_add_f32_e32 v89, v89, v90
	s_waitcnt lgkmcnt(0)
	v_lshlrev_b32_e32 v90, 16, v102
	v_and_b32_e32 v91, 0xffff0000, v102
	v_add_f32_e32 v90, v90, v91
	v_lshlrev_b32_e32 v91, 16, v103
	v_and_b32_e32 v92, 0xffff0000, v103
	v_add_f32_e32 v91, v91, v92
	v_add_f32_e32 v90, v90, v91
	v_lshlrev_b32_e32 v91, 16, v104
	v_and_b32_e32 v92, 0xffff0000, v104
	v_add_f32_e32 v91, v91, v92
	v_add_f32_e32 v90, v91, v90
	v_lshlrev_b32_e32 v91, 16, v105
	v_and_b32_e32 v92, 0xffff0000, v105
	v_add_f32_e32 v91, v91, v92
	s_cselect_b32 s84, s84, s90
	ds_read_b128 v[92:95], v182
	s_add_i32 s84, s84, s89
	v_or_b32_e32 v96, s84, v200
	v_ashrrev_i32_e32 v97, 31, v96
	v_lshlrev_b64 v[96:97], 11, v[96:97]
	v_lshl_add_u64 v[100:101], v[146:147], 0, v[96:97]
	ds_read_b128 v[96:99], v182 offset:64
	s_waitcnt lgkmcnt(1)
	v_mul_f32_e32 v84, v84, v92
	v_mul_f32_e32 v80, v80, v92
	v_cvt_pk_bf16_f32 v84, v84, v84
	global_store_short v[100:101], v84, off
	v_cvt_pk_bf16_f32 v80, v80, v80
	global_store_short v[100:101], v80, off offset:32
	v_or_b32_e32 v100, s84, v201
	v_ashrrev_i32_e32 v101, 31, v100
	v_lshlrev_b64 v[100:101], 11, v[100:101]
	v_mul_f32_e32 v80, v85, v93
	v_lshl_add_u64 v[100:101], v[146:147], 0, v[100:101]
	v_cvt_pk_bf16_f32 v80, v80, v80
	global_store_short v[100:101], v80, off
	v_mul_f32_e32 v80, v81, v93
	v_cvt_pk_bf16_f32 v80, v80, v80
	global_store_short v[100:101], v80, off offset:32
	v_or_b32_e32 v80, s84, v203
	v_ashrrev_i32_e32 v81, 31, v80
	v_lshlrev_b64 v[80:81], 11, v[80:81]
	v_lshl_add_u64 v[80:81], v[146:147], 0, v[80:81]
	v_mul_f32_e32 v84, v86, v94
	v_mul_f32_e32 v82, v82, v94
	v_cvt_pk_bf16_f32 v84, v84, v84
	global_store_short v[80:81], v84, off
	v_cvt_pk_bf16_f32 v82, v82, v82
	global_store_short v[80:81], v82, off offset:32
	v_or_b32_e32 v80, s84, v204
	v_ashrrev_i32_e32 v81, 31, v80
	v_lshlrev_b64 v[80:81], 11, v[80:81]
	v_mul_f32_e32 v82, v87, v95
	v_lshl_add_u64 v[80:81], v[146:147], 0, v[80:81]
	v_cvt_pk_bf16_f32 v82, v82, v82
	global_store_short v[80:81], v82, off
	v_mul_f32_e32 v82, v83, v95
	v_cvt_pk_bf16_f32 v82, v82, v82
	global_store_short v[80:81], v82, off offset:32
	v_or_b32_e32 v80, s84, v205
	v_ashrrev_i32_e32 v81, 31, v80
	v_lshlrev_b64 v[80:81], 11, v[80:81]
	v_lshl_add_u64 v[80:81], v[146:147], 0, v[80:81]
	s_waitcnt lgkmcnt(0)
	v_mul_f32_e32 v76, v76, v96
	v_mul_f32_e32 v72, v72, v96
	v_cvt_pk_bf16_f32 v76, v76, v76
	global_store_short v[80:81], v76, off
	v_cvt_pk_bf16_f32 v72, v72, v72
	global_store_short v[80:81], v72, off offset:32
	v_or_b32_e32 v80, s84, v206
	v_ashrrev_i32_e32 v81, 31, v80
	v_lshlrev_b64 v[80:81], 11, v[80:81]
	v_mul_f32_e32 v72, v77, v97
	v_add_f32_e32 v90, v91, v90
	v_lshl_add_u64 v[80:81], v[146:147], 0, v[80:81]
	v_cvt_pk_bf16_f32 v72, v72, v72
	v_add_f32_e32 v89, v89, v90
	global_store_short v[80:81], v72, off
	v_mul_f32_e32 v72, v73, v97
	s_nop 1
	v_add_f32_dpp v89, v89, v89 quad_perm:[1,0,3,2] row_mask:0xf bank_mask:0xf
	v_cvt_pk_bf16_f32 v72, v72, v72
	global_store_short v[80:81], v72, off offset:32
	v_or_b32_e32 v72, s84, v207
	v_ashrrev_i32_e32 v73, 31, v72
	v_lshlrev_b64 v[72:73], 11, v[72:73]
	v_lshl_add_u64 v[72:73], v[146:147], 0, v[72:73]
	v_mul_f32_e32 v76, v78, v98
	v_mul_f32_e32 v74, v74, v98
	s_waitcnt lgkmcnt(0)
	s_nop 0
	v_cvt_pk_bf16_f32 v76, v76, v76
	global_store_short v[72:73], v76, off
	v_cvt_pk_bf16_f32 v74, v74, v74
	global_store_short v[72:73], v74, off offset:32
	v_or_b32_e32 v72, s84, v208
	v_mov_b32_dpp v90, v89 quad_perm:[2,3,0,1] row_mask:0xf bank_mask:0xf
	v_ashrrev_i32_e32 v73, 31, v72
	v_lshlrev_b64 v[72:73], 11, v[72:73]
	v_mul_f32_e32 v74, v79, v99
	v_lshl_add_u64 v[72:73], v[146:147], 0, v[72:73]
	v_cvt_pk_bf16_f32 v74, v74, v74
	global_store_short v[72:73], v74, off
	v_mul_f32_e32 v74, v75, v99
	v_cvt_pk_bf16_f32 v76, v64, v65
	v_cvt_pk_bf16_f32 v74, v74, v74
	global_store_short v[72:73], v74, off offset:32
	s_waitcnt lgkmcnt(0)
	ds_read_b32 v245, v134
	v_cvt_pk_bf16_f32 v72, v56, v57
	v_cvt_pk_bf16_f32 v73, v58, v59
	v_cvt_pk_bf16_f32 v77, v66, v67
	ds_write2_b64 v217, v[72:73], v[76:77] offset1:4
	v_add_u32_e32 v76, 0x1000, v217
	v_cvt_pk_bf16_f32 v74, v60, v61
	v_cvt_pk_bf16_f32 v75, v62, v63
	v_cvt_pk_bf16_f32 v72, v68, v69
	v_cvt_pk_bf16_f32 v73, v70, v71
	ds_write2_b64 v76, v[74:75], v[72:73] offset0:32 offset1:36
	s_and_saveexec_b64 s[86:87], s[6:7]
	s_cbranch_execz .LBB0_201
	s_waitcnt lgkmcnt(2)
	v_add_f32_e32 v72, v89, v90
	v_mov_b32_e32 v73, v245
	v_fmac_f32_e32 v72, v88, v73
	ds_write_b32 v134, v72
	s_branch .LBB0_201
